# phase header: both scalar-load batches issued before one wait; ERES1 row-1 second half waits for its loads only (vmcnt(0)->vmcnt(3), newest store acks no longer awaited)
# baseline (speedup 1.0000x reference)
.LBB0_40:
	s_bitcmp1_b32 s3, 0
	s_cselect_b64 s[16:17], -1, 0
	s_and_b64 vcc, exec, s[16:17]
	s_cbranch_vccnz .LBB0_9
	s_mov_b64 s[26:27], s[0:1]
	v_mov_b32_e32 v208, v228
	s_load_dword s12, s[0:1], 0x78
	s_mov_b32 s28, s70
	s_nop 0
	s_load_dwordx16 s[52:67], s[26:27], 0x0
	s_load_dwordx2 s[24:25], s[26:27], 0x60
	s_load_dwordx8 s[36:43], s[26:27], 0x40
	s_lshl_b32 s2, s14, 1
	s_add_i32 s6, s13, -4
	s_cmp_lt_u32 s6, 3
	s_cselect_b64 s[16:17], -1, 0
	v_cndmask_b32_e64 v0, 0, 1, s[16:17]
	s_waitcnt lgkmcnt(0)
	v_writelane_b32 v255, s36, 21
	v_readfirstlane_b32 s6, v0
	s_or_b32 s2, s2, s6
	v_writelane_b32 v255, s37, 22
	v_writelane_b32 v255, s38, 23
	s_add_i32 s2, s2, -1
	v_writelane_b32 v255, s39, 24
	s_cmp_lt_u32 s2, 4
	v_writelane_b32 v255, s40, 25
	s_cselect_b64 s[30:31], -1, 0
	v_writelane_b32 v255, s41, 26
	s_and_b64 s[16:17], s[30:31], exec
	v_writelane_b32 v255, s42, 27
	s_cselect_b32 s2, 0x1a0fa400, 0
	v_writelane_b32 v255, s43, 28
	s_add_u32 s36, s24, s2
	s_addc_u32 s37, s25, 0
	s_and_b64 s[16:17], s[30:31], exec
	s_cselect_b32 s2, s71, 0x19680000
	s_add_u32 s86, s24, s2
	s_addc_u32 s87, s25, 0
	s_add_u32 s84, s24, 0x8100000
	s_addc_u32 s85, s25, 0
	s_ashr_i32 s82, s14, 1
	s_cmp_lt_i32 s13, 5
	s_mov_b64 s[26:27], -1
	s_cbranch_scc1 .LBB0_229
	s_cmp_lt_i32 s13, 7
	s_cbranch_scc1 .LBB0_46
	s_cmp_gt_i32 s13, 7
	s_cbranch_scc0 .LBB0_47
	s_cmp_gt_i32 s13, 8
	s_cbranch_scc0 .LBB0_48
	s_cmp_eq_u32 s13, 9
	s_cselect_b64 s[40:41], -1, 0
	s_cbranch_execz .LBB0_49
	s_branch .LBB0_65

.LBB0_136:
	v_mov_b32_e32 v39, v38
	s_waitcnt vmcnt(3)
	v_lshlrev_b32_e32 v28, 16, v18
	v_and_b32_e32 v29, 0xffff0000, v18
	v_lshlrev_b32_e32 v18, 16, v19
	v_and_b32_e32 v19, 0xffff0000, v19
	v_lshlrev_b32_e32 v26, 16, v22
	v_and_b32_e32 v27, 0xffff0000, v22
	v_pk_mul_f32 v[28:29], v[38:39], v[28:29]
	v_lshlrev_b32_e32 v22, 16, v23
	v_and_b32_e32 v23, 0xffff0000, v23
	v_pk_mul_f32 v[18:19], v[38:39], v[18:19]
	v_pk_fma_f32 v[26:27], v[10:11], v[28:29], v[26:27]
	v_pk_fma_f32 v[28:29], v[12:13], v[18:19], v[22:23]
	v_lshlrev_b32_e32 v22, 16, v20
	v_and_b32_e32 v23, 0xffff0000, v20
	v_lshlrev_b32_e32 v18, 16, v24
	v_and_b32_e32 v19, 0xffff0000, v24
	v_pk_mul_f32 v[22:23], v[38:39], v[22:23]
	v_lshlrev_b32_e32 v20, 16, v21
	v_and_b32_e32 v21, 0xffff0000, v21
	v_pk_fma_f32 v[18:19], v[2:3], v[22:23], v[18:19]
	v_lshlrev_b32_e32 v22, 16, v25
	v_and_b32_e32 v23, 0xffff0000, v25
	v_pk_mul_f32 v[20:21], v[38:39], v[20:21]
	s_and_b64 vcc, exec, s[44:45]
	v_pk_fma_f32 v[20:21], v[4:5], v[20:21], v[22:23]
	s_mov_b64 s[46:47], -1
	s_cbranch_vccz .LBB0_139
	s_andn2_b64 vcc, exec, s[46:47]
	s_cbranch_vccz .LBB0_140
